# all four buffer-overlay seams (WOA-UP0, DN0-PP0, WOB-UP1, DN1-PP1) group-scoped with cross-group arrival waits; GATE0-QKV also waits for the K/V overlay owners
# speedup vs baseline: 1.0035x; 1.0001x over previous
.LBB0_768:
	v_readlane_b32 s0, v249, 4
	v_readlane_b32 s1, v249, 5
	s_cmp_lt_i32 s1, 5
	s_mov_b64 s[0:1], -1
	s_cbranch_scc0 .LBB0_770
	s_waitcnt vmcnt(0) lgkmcnt(0)
	s_barrier
	s_mov_b64 s[0:1], 0
.LBB0_770:
	s_andn2_b64 vcc, exec, s[0:1]
	s_cbranch_vccnz .LBB0_837
	v_readlane_b32 s0, v249, 4
	v_readlane_b32 s1, v249, 5
	s_cmpk_lt_u32 s1, 0x3e9
	s_mov_b64 s[0:1], -1
	s_cbranch_scc0 .LBB0_825
	v_readlane_b32 s2, v249, 2
	s_cmpk_eq_i32 s2, 0x100
	s_cbranch_scc0 .Lg3_xcd
	s_waitcnt vmcnt(0)
	s_waitcnt vmcnt(0) lgkmcnt(0)
	s_barrier
	s_mov_b64 s[0:1], exec
	v_readlane_b32 s2, v249, 10
	v_readlane_b32 s3, v249, 11
	s_and_b64 s[2:3], s[0:1], s[2:3]
	s_mov_b64 exec, s[2:3]
	s_cbranch_execz .Lg3_BB0_1004
	s_lshl_b32 s2, s81, 8
	s_and_b32 s2, s2, 0x3f00
	s_mov_b64 s[4:5], exec
	s_add_u32 s2, s82, s2
	s_addc_u32 s3, s83, 0
	buffer_wbl2 sc1

.Lg3_BB0_1003:
	s_or_b64 exec, exec, s[4:5]
	s_and_b32 s4, s81, 7
	s_lshl_b32 s4, s4, 3
	s_bfe_u32 s5, s81, 0x30003
	s_add_i32 s4, s4, s5
	s_lshl_b32 s12, s4, 1
	s_mov_b32 s13, 2
	s_cmp_lt_u32 s4, 32
	s_cbranch_scc1 .Lg3_xdep
	s_sub_u32 s12, s4, 32
	s_lshl_b32 s12, s12, 2
	s_mov_b32 s13, 4
	s_cmp_lt_u32 s4, 48
	s_cbranch_scc1 .Lg3_xdep
	s_mov_b32 s13, 0
.Lg3_xdep:
	s_mov_b32 s14, -1
	v_mov_b32_e32 v1, 0
	s_mov_b32 s9, 12
	s_mov_b32 s8, 0

.Lg5_BB0_1003:
	s_or_b64 exec, exec, s[4:5]
	s_and_b32 s4, s81, 7
	s_lshl_b32 s4, s4, 3
	s_bfe_u32 s5, s81, 0x30003
	s_add_i32 s4, s4, s5
	s_lshr_b32 s12, s4, 2
	s_mov_b32 s13, 1
	s_add_i32 s14, s12, 48
	v_mov_b32_e32 v1, 0
	s_mov_b32 s9, 20
	s_mov_b32 s8, 0

.Lg7_BB0_1003:
	s_or_b64 exec, exec, s[4:5]
	s_and_b32 s4, s81, 7
	s_lshl_b32 s4, s4, 3
	s_bfe_u32 s5, s81, 0x30003
	s_add_i32 s4, s4, s5
	s_lshr_b32 s12, s4, 2
	s_add_i32 s14, s12, 32
	s_add_i32 s12, s12, 16
	s_mov_b32 s13, 1
	v_mov_b32_e32 v1, 0
	s_mov_b32 s9, 20
	s_mov_b32 s8, 0

.LBB0_1904:
	v_readlane_b32 s0, v249, 4
	v_readlane_b32 s1, v249, 5
	s_cmp_lt_i32 s1, 12
	s_mov_b64 s[0:1], -1
	s_cbranch_scc0 .LBB0_1906
	s_waitcnt vmcnt(0) lgkmcnt(0)
	s_barrier
	s_mov_b64 s[0:1], 0
.LBB0_1906:
	s_andn2_b64 vcc, exec, s[0:1]
	s_cbranch_vccnz .LBB0_1973
	v_readlane_b32 s0, v249, 4
	v_readlane_b32 s1, v249, 5
	s_cmpk_lt_u32 s1, 0x3e9
	s_mov_b64 s[0:1], -1
	s_cbranch_scc0 .LBB0_1961
	v_readlane_b32 s2, v249, 2
	s_cmpk_eq_i32 s2, 0x100
	s_cbranch_scc0 .Lg10_xcd
	s_waitcnt vmcnt(0)
	s_waitcnt vmcnt(0) lgkmcnt(0)
	s_barrier
	s_mov_b64 s[0:1], exec
	v_readlane_b32 s2, v249, 10
	v_readlane_b32 s3, v249, 11
	s_and_b64 s[2:3], s[0:1], s[2:3]
	s_mov_b64 exec, s[2:3]
	s_cbranch_execz .Lg10_BB0_1004
	s_lshl_b32 s2, s81, 8
	s_and_b32 s2, s2, 0x3f00
	s_mov_b64 s[4:5], exec
	s_add_u32 s2, s82, s2
	s_addc_u32 s3, s83, 0
	buffer_wbl2 sc1

.Lg10_BB0_1003:
	s_or_b64 exec, exec, s[4:5]
	s_and_b32 s4, s81, 7
	s_lshl_b32 s4, s4, 3
	s_bfe_u32 s5, s81, 0x30003
	s_add_i32 s4, s4, s5
	s_and_b32 s12, s4, 15
	s_lshl_b32 s12, s12, 2
	s_mov_b32 s13, 4
	s_mov_b32 s14, -1
	v_mov_b32_e32 v1, 0
	s_mov_b32 s9, 28
	s_mov_b32 s8, 0

.Lg12_BB0_1003:
	s_or_b64 exec, exec, s[4:5]
	s_and_b32 s4, s81, 7
	s_lshl_b32 s4, s4, 3
	s_bfe_u32 s5, s81, 0x30003
	s_add_i32 s4, s4, s5
	s_lshr_b32 s12, s4, 2
	s_mov_b32 s13, 1
	s_mov_b32 s14, -1
	v_mov_b32_e32 v1, 0
	s_mov_b32 s9, 36
	s_mov_b32 s8, 0
